# m34 + index emit pass: the four threshold compares of a tile group write four SGPR pairs and are issued before their selects (no hazard pads), and the tile's key position add moves into the rare list-
# baseline (speedup 1.0000x reference)
.LBB0_2327:
	v_add_u32_e32 v2, 0, v4
	v_add_u32_e32 v2, 0x22000, v2
	ds_read2_b32 v[6:7], v2 offset1:2
	s_add_i32 s0, 0, 0x20000
	v_lshl_add_u32 v4, v167, 9, s0
	v_and_b32_e32 v207, 28, v41
	v_ashrrev_i32_e32 v203, 5, v41
	v_lshlrev_b32_e64 v204, v207, 1
	v_lshlrev_b32_e64 v205, v207, 2
	v_lshlrev_b32_e64 v206, v207, 4
	v_lshlrev_b32_e64 v207, v207, 8
	v_lshl_add_u32 v203, v203, 2, v4
	s_mov_b32 s0, 0x3fffff
	s_waitcnt lgkmcnt(0)
	v_lshlrev_b32_e32 v3, 10, v6
	v_add_u32_e32 v2, 0x400, v3
	v_cmp_ne_u32_e32 vcc, s0, v6
	v_cmp_ne_u32_e64 s[40:41], 0, v7
	v_readlane_b32 s0, v251, 33
	v_cndmask_b32_e32 v2, -1, v2, vcc
	v_cndmask_b32_e64 v5, 1, v2, s[40:41]
	s_and_b64 vcc, exec, s[28:29]
	v_lshl_add_u32 v2, v167, 2, s0
	s_cbranch_vccnz .LBB0_2344
	v_cmp_ge_u32_e64 s[42:43], v171, v5
	v_cmp_lt_u32_e64 s[44:45], v170, v5
	v_cmp_lt_u32_e64 s[46:47], v169, v5
	v_cmp_lt_u32_e64 s[48:49], v168, v5
	v_cndmask_b32_e64 v6, 0, v204, s[42:43]
	v_cndmask_b32_e64 v7, v205, 0, s[44:45]
	v_cndmask_b32_e64 v208, v206, 0, s[46:47]
	v_cndmask_b32_e64 v8, v207, 0, s[48:49]
	v_or_b32_e32 v6, v7, v6
	v_or3_b32 v6, v6, v208, v8
	v_cmp_ne_u32_e32 vcc, 0, v6
	s_and_saveexec_b64 s[0:1], vcc
	ds_or_b32 v203, v6
	s_or_b64 exec, exec, s[0:1]
	v_xor_b32_e32 v7, v3, v169
	v_xor_b32_e32 v6, v3, v168
	v_xor_b32_e32 v9, v3, v171
	v_xor_b32_e32 v8, v3, v170
	v_min_u32_e32 v10, v7, v6
	v_min3_u32 v10, v9, v8, v10
	v_cmp_gt_u32_e32 vcc, s27, v10
	s_and_b64 s[8:9], s[40:41], vcc
	s_and_saveexec_b64 s[0:1], s[8:9]
	s_cbranch_execz .LBB0_2343
	v_cmp_gt_u32_e32 vcc, s27, v9
	s_and_saveexec_b64 s[8:9], vcc
	s_cbranch_execz .LBB0_2334
	ds_add_rtn_u32 v9, v2, v186
	s_waitcnt lgkmcnt(0)
	v_cmp_gt_u32_e32 vcc, 64, v9
	s_and_b64 exec, exec, vcc
	v_lshlrev_b32_e32 v10, 12, v171
	s_mov_b32 s7, 0x3ff000
	v_lshl_add_u32 v9, v9, 2, v40
	v_and_or_b32 v10, v10, s7, v41
	ds_write_b32 v9, v10

.LBB0_2344:
	s_cmp_lt_i32 s77, 8
	s_cbranch_scc1 .LBB0_2600
	v_cmp_ge_u32_e64 s[42:43], v166, v5
	v_cmp_lt_u32_e64 s[44:45], v165, v5
	v_cmp_lt_u32_e64 s[46:47], v164, v5
	v_cmp_lt_u32_e64 s[48:49], v163, v5
	v_cndmask_b32_e64 v7, 0, v204, s[42:43]
	v_cndmask_b32_e64 v8, v205, 0, s[44:45]
	v_cndmask_b32_e64 v208, v206, 0, s[46:47]
	v_cndmask_b32_e64 v9, v207, 0, s[48:49]
	v_or_b32_e32 v7, v8, v7
	v_or3_b32 v7, v7, v208, v9
	v_cmp_ne_u32_e32 vcc, 0, v7
	s_and_saveexec_b64 s[0:1], vcc
	ds_or_b32 v203, v7 offset:16
	s_or_b64 exec, exec, s[0:1]
	v_xor_b32_e32 v8, v3, v164
	v_xor_b32_e32 v7, v3, v163
	v_xor_b32_e32 v10, v3, v166
	v_xor_b32_e32 v9, v3, v165
	v_min_u32_e32 v11, v8, v7
	v_min3_u32 v11, v10, v9, v11
	v_cmp_gt_u32_e32 vcc, s27, v11
	s_and_b64 s[8:9], s[40:41], vcc
	s_and_saveexec_b64 s[0:1], s[8:9]
	s_cbranch_execz .LBB0_2360
	v_add_u32_e32 v6, 0x80, v41
	v_cmp_gt_u32_e32 vcc, s27, v10
	s_and_saveexec_b64 s[8:9], vcc
	s_cbranch_execz .LBB0_2351
	ds_add_rtn_u32 v10, v2, v186
	s_waitcnt lgkmcnt(0)
	v_cmp_gt_u32_e32 vcc, 64, v10
	s_and_b64 exec, exec, vcc
	v_lshlrev_b32_e32 v11, 12, v166
	s_mov_b32 s7, 0x3ff000
	v_lshl_add_u32 v10, v10, 2, v40
	v_and_or_b32 v11, v11, s7, v6
	ds_write_b32 v10, v11

.LBB0_2362:
	v_cmp_ge_u32_e64 s[42:43], v158, v5
	v_cmp_lt_u32_e64 s[44:45], v157, v5
	v_cmp_lt_u32_e64 s[46:47], v156, v5
	v_cmp_lt_u32_e64 s[48:49], v155, v5
	v_cndmask_b32_e64 v7, 0, v204, s[42:43]
	v_cndmask_b32_e64 v8, v205, 0, s[44:45]
	v_cndmask_b32_e64 v208, v206, 0, s[46:47]
	v_cndmask_b32_e64 v9, v207, 0, s[48:49]
	v_or_b32_e32 v7, v8, v7
	v_or3_b32 v7, v7, v208, v9
	v_cmp_ne_u32_e32 vcc, 0, v7
	s_and_saveexec_b64 s[0:1], vcc
	ds_or_b32 v203, v7 offset:48
	s_or_b64 exec, exec, s[0:1]
	v_xor_b32_e32 v8, v3, v156
	v_xor_b32_e32 v7, v3, v155
	v_xor_b32_e32 v10, v3, v158
	v_xor_b32_e32 v9, v3, v157
	v_min_u32_e32 v11, v8, v7
	v_min3_u32 v11, v10, v9, v11
	v_cmp_gt_u32_e32 vcc, s27, v11
	s_and_b64 s[8:9], s[40:41], vcc
	s_and_saveexec_b64 s[0:1], s[8:9]
	s_cbranch_execz .LBB0_2377
	v_add_u32_e32 v6, 0x180, v41
	v_cmp_gt_u32_e32 vcc, s27, v10
	s_and_saveexec_b64 s[8:9], vcc
	s_cbranch_execz .LBB0_2368
	ds_add_rtn_u32 v10, v2, v186
	s_waitcnt lgkmcnt(0)
	v_cmp_gt_u32_e32 vcc, 64, v10
	s_and_b64 exec, exec, vcc
	v_lshlrev_b32_e32 v11, 12, v158
	s_mov_b32 s7, 0x3ff000
	v_lshl_add_u32 v10, v10, 2, v40
	v_and_or_b32 v11, v11, s7, v6
	ds_write_b32 v10, v11

.LBB0_2379:
	v_cmp_ge_u32_e64 s[42:43], v150, v5
	v_cmp_lt_u32_e64 s[44:45], v149, v5
	v_cmp_lt_u32_e64 s[46:47], v148, v5
	v_cmp_lt_u32_e64 s[48:49], v147, v5
	v_cndmask_b32_e64 v7, 0, v204, s[42:43]
	v_cndmask_b32_e64 v8, v205, 0, s[44:45]
	v_cndmask_b32_e64 v208, v206, 0, s[46:47]
	v_cndmask_b32_e64 v9, v207, 0, s[48:49]
	v_or_b32_e32 v7, v8, v7
	v_or3_b32 v7, v7, v208, v9
	v_cmp_ne_u32_e32 vcc, 0, v7
	s_and_saveexec_b64 s[0:1], vcc
	ds_or_b32 v203, v7 offset:80
	s_or_b64 exec, exec, s[0:1]
	v_xor_b32_e32 v8, v3, v148
	v_xor_b32_e32 v7, v3, v147
	v_xor_b32_e32 v10, v3, v150
	v_xor_b32_e32 v9, v3, v149
	v_min_u32_e32 v11, v8, v7
	v_min3_u32 v11, v10, v9, v11
	v_cmp_gt_u32_e32 vcc, s27, v11
	s_and_b64 s[8:9], s[40:41], vcc
	s_and_saveexec_b64 s[0:1], s[8:9]
	s_cbranch_execz .LBB0_2394
	v_add_u32_e32 v6, 0x280, v41
	v_cmp_gt_u32_e32 vcc, s27, v10
	s_and_saveexec_b64 s[8:9], vcc
	s_cbranch_execz .LBB0_2385
	ds_add_rtn_u32 v10, v2, v186
	s_waitcnt lgkmcnt(0)
	v_cmp_gt_u32_e32 vcc, 64, v10
	s_and_b64 exec, exec, vcc
	v_lshlrev_b32_e32 v11, 12, v150
	s_mov_b32 s7, 0x3ff000
	v_lshl_add_u32 v10, v10, 2, v40
	v_and_or_b32 v11, v11, s7, v6
	ds_write_b32 v10, v11

.LBB0_2396:
	v_cmp_ge_u32_e64 s[42:43], v142, v5
	v_cmp_lt_u32_e64 s[44:45], v141, v5
	v_cmp_lt_u32_e64 s[46:47], v140, v5
	v_cmp_lt_u32_e64 s[48:49], v139, v5
	v_cndmask_b32_e64 v7, 0, v204, s[42:43]
	v_cndmask_b32_e64 v8, v205, 0, s[44:45]
	v_cndmask_b32_e64 v208, v206, 0, s[46:47]
	v_cndmask_b32_e64 v9, v207, 0, s[48:49]
	v_or_b32_e32 v7, v8, v7
	v_or3_b32 v7, v7, v208, v9
	v_cmp_ne_u32_e32 vcc, 0, v7
	s_and_saveexec_b64 s[0:1], vcc
	ds_or_b32 v203, v7 offset:112
	s_or_b64 exec, exec, s[0:1]
	v_xor_b32_e32 v8, v3, v140
	v_xor_b32_e32 v7, v3, v139
	v_xor_b32_e32 v10, v3, v142
	v_xor_b32_e32 v9, v3, v141
	v_min_u32_e32 v11, v8, v7
	v_min3_u32 v11, v10, v9, v11
	v_cmp_gt_u32_e32 vcc, s27, v11
	s_and_b64 s[8:9], s[40:41], vcc
	s_and_saveexec_b64 s[0:1], s[8:9]
	s_cbranch_execz .LBB0_2411
	v_add_u32_e32 v6, 0x380, v41
	v_cmp_gt_u32_e32 vcc, s27, v10
	s_and_saveexec_b64 s[8:9], vcc
	s_cbranch_execz .LBB0_2402
	ds_add_rtn_u32 v10, v2, v186
	s_waitcnt lgkmcnt(0)
	v_cmp_gt_u32_e32 vcc, 64, v10
	s_and_b64 exec, exec, vcc
	v_lshlrev_b32_e32 v11, 12, v142
	s_mov_b32 s7, 0x3ff000
	v_lshl_add_u32 v10, v10, 2, v40
	v_and_or_b32 v11, v11, s7, v6
	ds_write_b32 v10, v11

.LBB0_2413:
	v_cmp_ge_u32_e64 s[42:43], v134, v5
	v_cmp_lt_u32_e64 s[44:45], v133, v5
	v_cmp_lt_u32_e64 s[46:47], v132, v5
	v_cmp_lt_u32_e64 s[48:49], v131, v5
	v_cndmask_b32_e64 v7, 0, v204, s[42:43]
	v_cndmask_b32_e64 v8, v205, 0, s[44:45]
	v_cndmask_b32_e64 v208, v206, 0, s[46:47]
	v_cndmask_b32_e64 v9, v207, 0, s[48:49]
	v_or_b32_e32 v7, v8, v7
	v_or3_b32 v7, v7, v208, v9
	v_cmp_ne_u32_e32 vcc, 0, v7
	s_and_saveexec_b64 s[0:1], vcc
	ds_or_b32 v203, v7 offset:144
	s_or_b64 exec, exec, s[0:1]
	v_xor_b32_e32 v8, v3, v132
	v_xor_b32_e32 v7, v3, v131
	v_xor_b32_e32 v10, v3, v134
	v_xor_b32_e32 v9, v3, v133
	v_min_u32_e32 v11, v8, v7
	v_min3_u32 v11, v10, v9, v11
	v_cmp_gt_u32_e32 vcc, s27, v11
	s_and_b64 s[8:9], s[40:41], vcc
	s_and_saveexec_b64 s[0:1], s[8:9]
	s_cbranch_execz .LBB0_2428
	v_add_u32_e32 v6, 0x480, v41
	v_cmp_gt_u32_e32 vcc, s27, v10
	s_and_saveexec_b64 s[8:9], vcc
	s_cbranch_execz .LBB0_2419
	ds_add_rtn_u32 v10, v2, v186
	s_waitcnt lgkmcnt(0)
	v_cmp_gt_u32_e32 vcc, 64, v10
	s_and_b64 exec, exec, vcc
	v_lshlrev_b32_e32 v11, 12, v134
	s_mov_b32 s7, 0x3ff000
	v_lshl_add_u32 v10, v10, 2, v40
	v_and_or_b32 v11, v11, s7, v6
	ds_write_b32 v10, v11

.LBB0_2430:
	v_cmp_ge_u32_e64 s[42:43], v126, v5
	v_cmp_lt_u32_e64 s[44:45], v125, v5
	v_cmp_lt_u32_e64 s[46:47], v124, v5
	v_cmp_lt_u32_e64 s[48:49], v123, v5
	v_cndmask_b32_e64 v7, 0, v204, s[42:43]
	v_cndmask_b32_e64 v8, v205, 0, s[44:45]
	v_cndmask_b32_e64 v208, v206, 0, s[46:47]
	v_cndmask_b32_e64 v9, v207, 0, s[48:49]
	v_or_b32_e32 v7, v8, v7
	v_or3_b32 v7, v7, v208, v9
	v_cmp_ne_u32_e32 vcc, 0, v7
	s_and_saveexec_b64 s[0:1], vcc
	ds_or_b32 v203, v7 offset:176
	s_or_b64 exec, exec, s[0:1]
	v_xor_b32_e32 v8, v3, v124
	v_xor_b32_e32 v7, v3, v123
	v_xor_b32_e32 v10, v3, v126
	v_xor_b32_e32 v9, v3, v125
	v_min_u32_e32 v11, v8, v7
	v_min3_u32 v11, v10, v9, v11
	v_cmp_gt_u32_e32 vcc, s27, v11
	s_and_b64 s[8:9], s[40:41], vcc
	s_and_saveexec_b64 s[0:1], s[8:9]
	s_cbranch_execz .LBB0_2445
	v_add_u32_e32 v6, 0x580, v41
	v_cmp_gt_u32_e32 vcc, s27, v10
	s_and_saveexec_b64 s[8:9], vcc
	s_cbranch_execz .LBB0_2436
	ds_add_rtn_u32 v10, v2, v186
	s_waitcnt lgkmcnt(0)
	v_cmp_gt_u32_e32 vcc, 64, v10
	s_and_b64 exec, exec, vcc
	v_lshlrev_b32_e32 v11, 12, v126
	s_mov_b32 s7, 0x3ff000
	v_lshl_add_u32 v10, v10, 2, v40
	v_and_or_b32 v11, v11, s7, v6
	ds_write_b32 v10, v11

.LBB0_2447:
	v_cmp_ge_u32_e64 s[42:43], v118, v5
	v_cmp_lt_u32_e64 s[44:45], v117, v5
	v_cmp_lt_u32_e64 s[46:47], v115, v5
	v_cmp_lt_u32_e64 s[48:49], v114, v5
	v_cndmask_b32_e64 v7, 0, v204, s[42:43]
	v_cndmask_b32_e64 v8, v205, 0, s[44:45]
	v_cndmask_b32_e64 v208, v206, 0, s[46:47]
	v_cndmask_b32_e64 v9, v207, 0, s[48:49]
	v_or_b32_e32 v7, v8, v7
	v_or3_b32 v7, v7, v208, v9
	v_cmp_ne_u32_e32 vcc, 0, v7
	s_and_saveexec_b64 s[0:1], vcc
	ds_or_b32 v203, v7 offset:208
	s_or_b64 exec, exec, s[0:1]
	v_xor_b32_e32 v8, v3, v115
	v_xor_b32_e32 v7, v3, v114
	v_xor_b32_e32 v10, v3, v118
	v_xor_b32_e32 v9, v3, v117
	v_min_u32_e32 v11, v8, v7
	v_min3_u32 v11, v10, v9, v11
	v_cmp_gt_u32_e32 vcc, s27, v11
	s_and_b64 s[8:9], s[40:41], vcc
	s_and_saveexec_b64 s[0:1], s[8:9]
	s_cbranch_execz .LBB0_2462
	v_add_u32_e32 v6, 0x680, v41
	v_cmp_gt_u32_e32 vcc, s27, v10
	s_and_saveexec_b64 s[8:9], vcc
	s_cbranch_execz .LBB0_2453
	ds_add_rtn_u32 v10, v2, v186
	s_waitcnt lgkmcnt(0)
	v_cmp_gt_u32_e32 vcc, 64, v10
	s_and_b64 exec, exec, vcc
	v_lshlrev_b32_e32 v11, 12, v118
	s_mov_b32 s7, 0x3ff000
	v_lshl_add_u32 v10, v10, 2, v40
	v_and_or_b32 v11, v11, s7, v6
	ds_write_b32 v10, v11

.LBB0_2464:
	v_cmp_ge_u32_e64 s[42:43], v109, v5
	v_cmp_lt_u32_e64 s[44:45], v108, v5
	v_cmp_lt_u32_e64 s[46:47], v107, v5
	v_cmp_lt_u32_e64 s[48:49], v105, v5
	v_cndmask_b32_e64 v7, 0, v204, s[42:43]
	v_cndmask_b32_e64 v8, v205, 0, s[44:45]
	v_cndmask_b32_e64 v208, v206, 0, s[46:47]
	v_cndmask_b32_e64 v9, v207, 0, s[48:49]
	v_or_b32_e32 v7, v8, v7
	v_or3_b32 v7, v7, v208, v9
	v_cmp_ne_u32_e32 vcc, 0, v7
	s_and_saveexec_b64 s[0:1], vcc
	ds_or_b32 v203, v7 offset:240
	s_or_b64 exec, exec, s[0:1]
	v_xor_b32_e32 v8, v3, v107
	v_xor_b32_e32 v7, v3, v105
	v_xor_b32_e32 v10, v3, v109
	v_xor_b32_e32 v9, v3, v108
	v_min_u32_e32 v11, v8, v7
	v_min3_u32 v11, v10, v9, v11
	v_cmp_gt_u32_e32 vcc, s27, v11
	s_and_b64 s[8:9], s[40:41], vcc
	s_and_saveexec_b64 s[0:1], s[8:9]
	s_cbranch_execz .LBB0_2479
	v_add_u32_e32 v6, 0x780, v41
	v_cmp_gt_u32_e32 vcc, s27, v10
	s_and_saveexec_b64 s[8:9], vcc
	s_cbranch_execz .LBB0_2470
	ds_add_rtn_u32 v10, v2, v186
	s_waitcnt lgkmcnt(0)
	v_cmp_gt_u32_e32 vcc, 64, v10
	s_and_b64 exec, exec, vcc
	v_lshlrev_b32_e32 v11, 12, v109
	s_mov_b32 s7, 0x3ff000
	v_lshl_add_u32 v10, v10, 2, v40
	v_and_or_b32 v11, v11, s7, v6
	ds_write_b32 v10, v11

.LBB0_2481:
	v_cmp_ge_u32_e64 s[42:43], v101, v5
	v_cmp_lt_u32_e64 s[44:45], v100, v5
	v_cmp_lt_u32_e64 s[46:47], v99, v5
	v_cmp_lt_u32_e64 s[48:49], v98, v5
	v_cndmask_b32_e64 v7, 0, v204, s[42:43]
	v_cndmask_b32_e64 v8, v205, 0, s[44:45]
	v_cndmask_b32_e64 v208, v206, 0, s[46:47]
	v_cndmask_b32_e64 v9, v207, 0, s[48:49]
	v_or_b32_e32 v7, v8, v7
	v_or3_b32 v7, v7, v208, v9
	v_cmp_ne_u32_e32 vcc, 0, v7
	s_and_saveexec_b64 s[0:1], vcc
	ds_or_b32 v203, v7 offset:272
	s_or_b64 exec, exec, s[0:1]
	v_xor_b32_e32 v8, v3, v99
	v_xor_b32_e32 v7, v3, v98
	v_xor_b32_e32 v10, v3, v101
	v_xor_b32_e32 v9, v3, v100
	v_min_u32_e32 v11, v8, v7
	v_min3_u32 v11, v10, v9, v11
	v_cmp_gt_u32_e32 vcc, s27, v11
	s_and_b64 s[8:9], s[40:41], vcc
	s_and_saveexec_b64 s[0:1], s[8:9]
	s_cbranch_execz .LBB0_2496
	v_add_u32_e32 v6, 0x880, v41
	v_cmp_gt_u32_e32 vcc, s27, v10
	s_and_saveexec_b64 s[8:9], vcc
	s_cbranch_execz .LBB0_2487
	ds_add_rtn_u32 v10, v2, v186
	s_waitcnt lgkmcnt(0)
	v_cmp_gt_u32_e32 vcc, 64, v10
	s_and_b64 exec, exec, vcc
	v_lshlrev_b32_e32 v11, 12, v101
	s_mov_b32 s7, 0x3ff000
	v_lshl_add_u32 v10, v10, 2, v40
	v_and_or_b32 v11, v11, s7, v6
	ds_write_b32 v10, v11

.LBB0_2498:
	v_cmp_ge_u32_e64 s[42:43], v93, v5
	v_cmp_lt_u32_e64 s[44:45], v92, v5
	v_cmp_lt_u32_e64 s[46:47], v91, v5
	v_cmp_lt_u32_e64 s[48:49], v90, v5
	v_cndmask_b32_e64 v7, 0, v204, s[42:43]
	v_cndmask_b32_e64 v8, v205, 0, s[44:45]
	v_cndmask_b32_e64 v208, v206, 0, s[46:47]
	v_cndmask_b32_e64 v9, v207, 0, s[48:49]
	v_or_b32_e32 v7, v8, v7
	v_or3_b32 v7, v7, v208, v9
	v_cmp_ne_u32_e32 vcc, 0, v7
	s_and_saveexec_b64 s[0:1], vcc
	ds_or_b32 v203, v7 offset:304
	s_or_b64 exec, exec, s[0:1]
	v_xor_b32_e32 v8, v3, v91
	v_xor_b32_e32 v7, v3, v90
	v_xor_b32_e32 v10, v3, v93
	v_xor_b32_e32 v9, v3, v92
	v_min_u32_e32 v11, v8, v7
	v_min3_u32 v11, v10, v9, v11
	v_cmp_gt_u32_e32 vcc, s27, v11
	s_and_b64 s[8:9], s[40:41], vcc
	s_and_saveexec_b64 s[0:1], s[8:9]
	s_cbranch_execz .LBB0_2513
	v_add_u32_e32 v6, 0x980, v41
	v_cmp_gt_u32_e32 vcc, s27, v10
	s_and_saveexec_b64 s[8:9], vcc
	s_cbranch_execz .LBB0_2504
	ds_add_rtn_u32 v10, v2, v186
	s_waitcnt lgkmcnt(0)
	v_cmp_gt_u32_e32 vcc, 64, v10
	s_and_b64 exec, exec, vcc
	v_lshlrev_b32_e32 v11, 12, v93
	s_mov_b32 s7, 0x3ff000
	v_lshl_add_u32 v10, v10, 2, v40
	v_and_or_b32 v11, v11, s7, v6
	ds_write_b32 v10, v11

.LBB0_2515:
	v_cmp_ge_u32_e64 s[42:43], v85, v5
	v_cmp_lt_u32_e64 s[44:45], v84, v5
	v_cmp_lt_u32_e64 s[46:47], v83, v5
	v_cmp_lt_u32_e64 s[48:49], v82, v5
	v_cndmask_b32_e64 v7, 0, v204, s[42:43]
	v_cndmask_b32_e64 v8, v205, 0, s[44:45]
	v_cndmask_b32_e64 v208, v206, 0, s[46:47]
	v_cndmask_b32_e64 v9, v207, 0, s[48:49]
	v_or_b32_e32 v7, v8, v7
	v_or3_b32 v7, v7, v208, v9
	v_cmp_ne_u32_e32 vcc, 0, v7
	s_and_saveexec_b64 s[0:1], vcc
	ds_or_b32 v203, v7 offset:336
	s_or_b64 exec, exec, s[0:1]
	v_xor_b32_e32 v8, v3, v83
	v_xor_b32_e32 v7, v3, v82
	v_xor_b32_e32 v10, v3, v85
	v_xor_b32_e32 v9, v3, v84
	v_min_u32_e32 v11, v8, v7
	v_min3_u32 v11, v10, v9, v11
	v_cmp_gt_u32_e32 vcc, s27, v11
	s_and_b64 s[8:9], s[40:41], vcc
	s_and_saveexec_b64 s[0:1], s[8:9]
	s_cbranch_execz .LBB0_2530
	v_add_u32_e32 v6, 0xa80, v41
	v_cmp_gt_u32_e32 vcc, s27, v10
	s_and_saveexec_b64 s[8:9], vcc
	s_cbranch_execz .LBB0_2521
	ds_add_rtn_u32 v10, v2, v186
	s_waitcnt lgkmcnt(0)
	v_cmp_gt_u32_e32 vcc, 64, v10
	s_and_b64 exec, exec, vcc
	v_lshlrev_b32_e32 v11, 12, v85
	s_mov_b32 s7, 0x3ff000
	v_lshl_add_u32 v10, v10, 2, v40
	v_and_or_b32 v11, v11, s7, v6
	ds_write_b32 v10, v11

.LBB0_2532:
	v_cmp_ge_u32_e64 s[42:43], v77, v5
	v_cmp_lt_u32_e64 s[44:45], v76, v5
	v_cmp_lt_u32_e64 s[46:47], v75, v5
	v_cmp_lt_u32_e64 s[48:49], v74, v5
	v_cndmask_b32_e64 v7, 0, v204, s[42:43]
	v_cndmask_b32_e64 v8, v205, 0, s[44:45]
	v_cndmask_b32_e64 v208, v206, 0, s[46:47]
	v_cndmask_b32_e64 v9, v207, 0, s[48:49]
	v_or_b32_e32 v7, v8, v7
	v_or3_b32 v7, v7, v208, v9
	v_cmp_ne_u32_e32 vcc, 0, v7
	s_and_saveexec_b64 s[0:1], vcc
	ds_or_b32 v203, v7 offset:368
	s_or_b64 exec, exec, s[0:1]
	v_xor_b32_e32 v8, v3, v75
	v_xor_b32_e32 v7, v3, v74
	v_xor_b32_e32 v10, v3, v77
	v_xor_b32_e32 v9, v3, v76
	v_min_u32_e32 v11, v8, v7
	v_min3_u32 v11, v10, v9, v11
	v_cmp_gt_u32_e32 vcc, s27, v11
	s_and_b64 s[8:9], s[40:41], vcc
	s_and_saveexec_b64 s[0:1], s[8:9]
	s_cbranch_execz .LBB0_2547
	v_add_u32_e32 v6, 0xb80, v41
	v_cmp_gt_u32_e32 vcc, s27, v10
	s_and_saveexec_b64 s[8:9], vcc
	s_cbranch_execz .LBB0_2538
	ds_add_rtn_u32 v10, v2, v186
	s_waitcnt lgkmcnt(0)
	v_cmp_gt_u32_e32 vcc, 64, v10
	s_and_b64 exec, exec, vcc
	v_lshlrev_b32_e32 v11, 12, v77
	s_mov_b32 s7, 0x3ff000
	v_lshl_add_u32 v10, v10, 2, v40
	v_and_or_b32 v11, v11, s7, v6
	ds_write_b32 v10, v11

.LBB0_2549:
	v_cmp_ge_u32_e64 s[42:43], v69, v5
	v_cmp_lt_u32_e64 s[44:45], v68, v5
	v_cmp_lt_u32_e64 s[46:47], v67, v5
	v_cmp_lt_u32_e64 s[48:49], v66, v5
	v_cndmask_b32_e64 v7, 0, v204, s[42:43]
	v_cndmask_b32_e64 v8, v205, 0, s[44:45]
	v_cndmask_b32_e64 v208, v206, 0, s[46:47]
	v_cndmask_b32_e64 v9, v207, 0, s[48:49]
	v_or_b32_e32 v7, v8, v7
	v_or3_b32 v7, v7, v208, v9
	v_cmp_ne_u32_e32 vcc, 0, v7
	s_and_saveexec_b64 s[0:1], vcc
	ds_or_b32 v203, v7 offset:400
	s_or_b64 exec, exec, s[0:1]
	v_xor_b32_e32 v8, v3, v67
	v_xor_b32_e32 v7, v3, v66
	v_xor_b32_e32 v10, v3, v69
	v_xor_b32_e32 v9, v3, v68
	v_min_u32_e32 v11, v8, v7
	v_min3_u32 v11, v10, v9, v11
	v_cmp_gt_u32_e32 vcc, s27, v11
	s_and_b64 s[8:9], s[40:41], vcc
	s_and_saveexec_b64 s[0:1], s[8:9]
	s_cbranch_execz .LBB0_2564
	v_add_u32_e32 v6, 0xc80, v41
	v_cmp_gt_u32_e32 vcc, s27, v10
	s_and_saveexec_b64 s[8:9], vcc
	s_cbranch_execz .LBB0_2555
	ds_add_rtn_u32 v10, v2, v186
	s_waitcnt lgkmcnt(0)
	v_cmp_gt_u32_e32 vcc, 64, v10
	s_and_b64 exec, exec, vcc
	v_lshlrev_b32_e32 v11, 12, v69
	s_mov_b32 s7, 0x3ff000
	v_lshl_add_u32 v10, v10, 2, v40
	v_and_or_b32 v11, v11, s7, v6
	ds_write_b32 v10, v11

.LBB0_2566:
	v_cmp_ge_u32_e64 s[42:43], v61, v5
	v_cmp_lt_u32_e64 s[44:45], v60, v5
	v_cmp_lt_u32_e64 s[46:47], v59, v5
	v_cmp_lt_u32_e64 s[48:49], v58, v5
	v_cndmask_b32_e64 v7, 0, v204, s[42:43]
	v_cndmask_b32_e64 v8, v205, 0, s[44:45]
	v_cndmask_b32_e64 v208, v206, 0, s[46:47]
	v_cndmask_b32_e64 v9, v207, 0, s[48:49]
	v_or_b32_e32 v7, v8, v7
	v_or3_b32 v7, v7, v208, v9
	v_cmp_ne_u32_e32 vcc, 0, v7
	s_and_saveexec_b64 s[0:1], vcc
	ds_or_b32 v203, v7 offset:432
	s_or_b64 exec, exec, s[0:1]
	v_xor_b32_e32 v8, v3, v59
	v_xor_b32_e32 v7, v3, v58
	v_xor_b32_e32 v10, v3, v61
	v_xor_b32_e32 v9, v3, v60
	v_min_u32_e32 v11, v8, v7
	v_min3_u32 v11, v10, v9, v11
	v_cmp_gt_u32_e32 vcc, s27, v11
	s_and_b64 s[8:9], s[40:41], vcc
	s_and_saveexec_b64 s[0:1], s[8:9]
	s_cbranch_execz .LBB0_2581
	v_add_u32_e32 v6, 0xd80, v41
	v_cmp_gt_u32_e32 vcc, s27, v10
	s_and_saveexec_b64 s[8:9], vcc
	s_cbranch_execz .LBB0_2572
	ds_add_rtn_u32 v10, v2, v186
	s_waitcnt lgkmcnt(0)
	v_cmp_gt_u32_e32 vcc, 64, v10
	s_and_b64 exec, exec, vcc
	v_lshlrev_b32_e32 v11, 12, v61
	s_mov_b32 s7, 0x3ff000
	v_lshl_add_u32 v10, v10, 2, v40
	v_and_or_b32 v11, v11, s7, v6
	ds_write_b32 v10, v11

.LBB0_2583:
	v_cmp_ge_u32_e64 s[42:43], v53, v5
	v_cmp_lt_u32_e64 s[44:45], v52, v5
	v_cmp_lt_u32_e64 s[46:47], v51, v5
	v_cmp_lt_u32_e64 s[48:49], v50, v5
	v_cndmask_b32_e64 v7, 0, v204, s[42:43]
	v_cndmask_b32_e64 v8, v205, 0, s[44:45]
	v_cndmask_b32_e64 v208, v206, 0, s[46:47]
	v_cndmask_b32_e64 v9, v207, 0, s[48:49]
	v_or_b32_e32 v7, v8, v7
	v_or3_b32 v7, v7, v208, v9
	v_cmp_ne_u32_e32 vcc, 0, v7
	s_and_saveexec_b64 s[0:1], vcc
	ds_or_b32 v203, v7 offset:464
	s_or_b64 exec, exec, s[0:1]
	v_xor_b32_e32 v8, v3, v51
	v_xor_b32_e32 v7, v3, v50
	v_xor_b32_e32 v10, v3, v53
	v_xor_b32_e32 v9, v3, v52
	v_min_u32_e32 v11, v8, v7
	v_min3_u32 v11, v10, v9, v11
	v_cmp_gt_u32_e32 vcc, s27, v11
	s_and_b64 s[8:9], s[40:41], vcc
	s_and_saveexec_b64 s[0:1], s[8:9]
	s_cbranch_execz .LBB0_2598
	v_add_u32_e32 v6, 0xe80, v41
	v_cmp_gt_u32_e32 vcc, s27, v10
	s_and_saveexec_b64 s[8:9], vcc
	s_cbranch_execz .LBB0_2589
	ds_add_rtn_u32 v10, v2, v186
	s_waitcnt lgkmcnt(0)
	v_cmp_gt_u32_e32 vcc, 64, v10
	s_and_b64 exec, exec, vcc
	v_lshlrev_b32_e32 v11, 12, v53
	s_mov_b32 s7, 0x3ff000
	v_lshl_add_u32 v10, v10, 2, v40
	v_and_or_b32 v11, v11, s7, v6
	ds_write_b32 v10, v11

.LBB0_2601:
	v_cmp_ge_u32_e64 s[42:43], v162, v5
	v_cmp_lt_u32_e64 s[44:45], v161, v5
	v_cmp_lt_u32_e64 s[46:47], v160, v5
	v_cmp_lt_u32_e64 s[48:49], v159, v5
	v_cndmask_b32_e64 v7, 0, v204, s[42:43]
	v_cndmask_b32_e64 v8, v205, 0, s[44:45]
	v_cndmask_b32_e64 v208, v206, 0, s[46:47]
	v_cndmask_b32_e64 v9, v207, 0, s[48:49]
	v_or_b32_e32 v7, v8, v7
	v_or3_b32 v7, v7, v208, v9
	v_cmp_ne_u32_e32 vcc, 0, v7
	s_and_saveexec_b64 s[0:1], vcc
	ds_or_b32 v203, v7 offset:32
	s_or_b64 exec, exec, s[0:1]
	v_xor_b32_e32 v8, v3, v160
	v_xor_b32_e32 v7, v3, v159
	v_xor_b32_e32 v10, v3, v162
	v_xor_b32_e32 v9, v3, v161
	v_min_u32_e32 v11, v8, v7
	v_min3_u32 v11, v10, v9, v11
	v_cmp_gt_u32_e32 vcc, s27, v11
	s_and_b64 s[8:9], s[40:41], vcc
	s_and_saveexec_b64 s[0:1], s[8:9]
	s_cbranch_execz .LBB0_2616
	v_add_u32_e32 v6, 0x100, v41
	v_cmp_gt_u32_e32 vcc, s27, v10
	s_and_saveexec_b64 s[8:9], vcc
	s_cbranch_execz .LBB0_2607
	ds_add_rtn_u32 v10, v2, v186
	s_waitcnt lgkmcnt(0)
	v_cmp_gt_u32_e32 vcc, 64, v10
	s_and_b64 exec, exec, vcc
	v_lshlrev_b32_e32 v11, 12, v162
	s_mov_b32 s7, 0x3ff000
	v_lshl_add_u32 v10, v10, 2, v40
	v_and_or_b32 v11, v11, s7, v6
	ds_write_b32 v10, v11

.LBB0_2618:
	v_cmp_ge_u32_e64 s[42:43], v154, v5
	v_cmp_lt_u32_e64 s[44:45], v153, v5
	v_cmp_lt_u32_e64 s[46:47], v152, v5
	v_cmp_lt_u32_e64 s[48:49], v151, v5
	v_cndmask_b32_e64 v7, 0, v204, s[42:43]
	v_cndmask_b32_e64 v8, v205, 0, s[44:45]
	v_cndmask_b32_e64 v208, v206, 0, s[46:47]
	v_cndmask_b32_e64 v9, v207, 0, s[48:49]
	v_or_b32_e32 v7, v8, v7
	v_or3_b32 v7, v7, v208, v9
	v_cmp_ne_u32_e32 vcc, 0, v7
	s_and_saveexec_b64 s[0:1], vcc
	ds_or_b32 v203, v7 offset:64
	s_or_b64 exec, exec, s[0:1]
	v_xor_b32_e32 v8, v3, v152
	v_xor_b32_e32 v7, v3, v151
	v_xor_b32_e32 v10, v3, v154
	v_xor_b32_e32 v9, v3, v153
	v_min_u32_e32 v11, v8, v7
	v_min3_u32 v11, v10, v9, v11
	v_cmp_gt_u32_e32 vcc, s27, v11
	s_and_b64 s[8:9], s[40:41], vcc
	s_and_saveexec_b64 s[0:1], s[8:9]
	s_cbranch_execz .LBB0_2633
	v_add_u32_e32 v6, 0x200, v41
	v_cmp_gt_u32_e32 vcc, s27, v10
	s_and_saveexec_b64 s[8:9], vcc
	s_cbranch_execz .LBB0_2624
	ds_add_rtn_u32 v10, v2, v186
	s_waitcnt lgkmcnt(0)
	v_cmp_gt_u32_e32 vcc, 64, v10
	s_and_b64 exec, exec, vcc
	v_lshlrev_b32_e32 v11, 12, v154
	s_mov_b32 s7, 0x3ff000
	v_lshl_add_u32 v10, v10, 2, v40
	v_and_or_b32 v11, v11, s7, v6
	ds_write_b32 v10, v11

.LBB0_2635:
	v_cmp_ge_u32_e64 s[42:43], v146, v5
	v_cmp_lt_u32_e64 s[44:45], v145, v5
	v_cmp_lt_u32_e64 s[46:47], v144, v5
	v_cmp_lt_u32_e64 s[48:49], v143, v5
	v_cndmask_b32_e64 v7, 0, v204, s[42:43]
	v_cndmask_b32_e64 v8, v205, 0, s[44:45]
	v_cndmask_b32_e64 v208, v206, 0, s[46:47]
	v_cndmask_b32_e64 v9, v207, 0, s[48:49]
	v_or_b32_e32 v7, v8, v7
	v_or3_b32 v7, v7, v208, v9
	v_cmp_ne_u32_e32 vcc, 0, v7
	s_and_saveexec_b64 s[0:1], vcc
	ds_or_b32 v203, v7 offset:96
	s_or_b64 exec, exec, s[0:1]
	v_xor_b32_e32 v8, v3, v144
	v_xor_b32_e32 v7, v3, v143
	v_xor_b32_e32 v10, v3, v146
	v_xor_b32_e32 v9, v3, v145
	v_min_u32_e32 v11, v8, v7
	v_min3_u32 v11, v10, v9, v11
	v_cmp_gt_u32_e32 vcc, s27, v11
	s_and_b64 s[8:9], s[40:41], vcc
	s_and_saveexec_b64 s[0:1], s[8:9]
	s_cbranch_execz .LBB0_2650
	v_add_u32_e32 v6, 0x300, v41
	v_cmp_gt_u32_e32 vcc, s27, v10
	s_and_saveexec_b64 s[8:9], vcc
	s_cbranch_execz .LBB0_2641
	ds_add_rtn_u32 v10, v2, v186
	s_waitcnt lgkmcnt(0)
	v_cmp_gt_u32_e32 vcc, 64, v10
	s_and_b64 exec, exec, vcc
	v_lshlrev_b32_e32 v11, 12, v146
	s_mov_b32 s7, 0x3ff000
	v_lshl_add_u32 v10, v10, 2, v40
	v_and_or_b32 v11, v11, s7, v6
	ds_write_b32 v10, v11

.LBB0_2652:
	v_cmp_ge_u32_e64 s[42:43], v138, v5
	v_cmp_lt_u32_e64 s[44:45], v137, v5
	v_cmp_lt_u32_e64 s[46:47], v136, v5
	v_cmp_lt_u32_e64 s[48:49], v135, v5
	v_cndmask_b32_e64 v7, 0, v204, s[42:43]
	v_cndmask_b32_e64 v8, v205, 0, s[44:45]
	v_cndmask_b32_e64 v208, v206, 0, s[46:47]
	v_cndmask_b32_e64 v9, v207, 0, s[48:49]
	v_or_b32_e32 v7, v8, v7
	v_or3_b32 v7, v7, v208, v9
	v_cmp_ne_u32_e32 vcc, 0, v7
	s_and_saveexec_b64 s[0:1], vcc
	ds_or_b32 v203, v7 offset:128
	s_or_b64 exec, exec, s[0:1]
	v_xor_b32_e32 v8, v3, v136
	v_xor_b32_e32 v7, v3, v135
	v_xor_b32_e32 v10, v3, v138
	v_xor_b32_e32 v9, v3, v137
	v_min_u32_e32 v11, v8, v7
	v_min3_u32 v11, v10, v9, v11
	v_cmp_gt_u32_e32 vcc, s27, v11
	s_and_b64 s[8:9], s[40:41], vcc
	s_and_saveexec_b64 s[0:1], s[8:9]
	s_cbranch_execz .LBB0_2667
	v_add_u32_e32 v6, 0x400, v41
	v_cmp_gt_u32_e32 vcc, s27, v10
	s_and_saveexec_b64 s[8:9], vcc
	s_cbranch_execz .LBB0_2658
	ds_add_rtn_u32 v10, v2, v186
	s_waitcnt lgkmcnt(0)
	v_cmp_gt_u32_e32 vcc, 64, v10
	s_and_b64 exec, exec, vcc
	v_lshlrev_b32_e32 v11, 12, v138
	s_mov_b32 s7, 0x3ff000
	v_lshl_add_u32 v10, v10, 2, v40
	v_and_or_b32 v11, v11, s7, v6
	ds_write_b32 v10, v11

.LBB0_2669:
	v_cmp_ge_u32_e64 s[42:43], v130, v5
	v_cmp_lt_u32_e64 s[44:45], v129, v5
	v_cmp_lt_u32_e64 s[46:47], v128, v5
	v_cmp_lt_u32_e64 s[48:49], v127, v5
	v_cndmask_b32_e64 v7, 0, v204, s[42:43]
	v_cndmask_b32_e64 v8, v205, 0, s[44:45]
	v_cndmask_b32_e64 v208, v206, 0, s[46:47]
	v_cndmask_b32_e64 v9, v207, 0, s[48:49]
	v_or_b32_e32 v7, v8, v7
	v_or3_b32 v7, v7, v208, v9
	v_cmp_ne_u32_e32 vcc, 0, v7
	s_and_saveexec_b64 s[0:1], vcc
	ds_or_b32 v203, v7 offset:160
	s_or_b64 exec, exec, s[0:1]
	v_xor_b32_e32 v8, v3, v128
	v_xor_b32_e32 v7, v3, v127
	v_xor_b32_e32 v10, v3, v130
	v_xor_b32_e32 v9, v3, v129
	v_min_u32_e32 v11, v8, v7
	v_min3_u32 v11, v10, v9, v11
	v_cmp_gt_u32_e32 vcc, s27, v11
	s_and_b64 s[8:9], s[40:41], vcc
	s_and_saveexec_b64 s[0:1], s[8:9]
	s_cbranch_execz .LBB0_2684
	v_add_u32_e32 v6, 0x500, v41
	v_cmp_gt_u32_e32 vcc, s27, v10
	s_and_saveexec_b64 s[8:9], vcc
	s_cbranch_execz .LBB0_2675
	ds_add_rtn_u32 v10, v2, v186
	s_waitcnt lgkmcnt(0)
	v_cmp_gt_u32_e32 vcc, 64, v10
	s_and_b64 exec, exec, vcc
	v_lshlrev_b32_e32 v11, 12, v130
	s_mov_b32 s7, 0x3ff000
	v_lshl_add_u32 v10, v10, 2, v40
	v_and_or_b32 v11, v11, s7, v6
	ds_write_b32 v10, v11

.LBB0_2686:
	v_cmp_ge_u32_e64 s[42:43], v122, v5
	v_cmp_lt_u32_e64 s[44:45], v121, v5
	v_cmp_lt_u32_e64 s[46:47], v120, v5
	v_cmp_lt_u32_e64 s[48:49], v119, v5
	v_cndmask_b32_e64 v7, 0, v204, s[42:43]
	v_cndmask_b32_e64 v8, v205, 0, s[44:45]
	v_cndmask_b32_e64 v208, v206, 0, s[46:47]
	v_cndmask_b32_e64 v9, v207, 0, s[48:49]
	v_or_b32_e32 v7, v8, v7
	v_or3_b32 v7, v7, v208, v9
	v_cmp_ne_u32_e32 vcc, 0, v7
	s_and_saveexec_b64 s[0:1], vcc
	ds_or_b32 v203, v7 offset:192
	s_or_b64 exec, exec, s[0:1]
	v_xor_b32_e32 v8, v3, v120
	v_xor_b32_e32 v7, v3, v119
	v_xor_b32_e32 v10, v3, v122
	v_xor_b32_e32 v9, v3, v121
	v_min_u32_e32 v11, v8, v7
	v_min3_u32 v11, v10, v9, v11
	v_cmp_gt_u32_e32 vcc, s27, v11
	s_and_b64 s[8:9], s[40:41], vcc
	s_and_saveexec_b64 s[0:1], s[8:9]
	s_cbranch_execz .LBB0_2701
	v_add_u32_e32 v6, 0x600, v41
	v_cmp_gt_u32_e32 vcc, s27, v10
	s_and_saveexec_b64 s[8:9], vcc
	s_cbranch_execz .LBB0_2692
	ds_add_rtn_u32 v10, v2, v186
	s_waitcnt lgkmcnt(0)
	v_cmp_gt_u32_e32 vcc, 64, v10
	s_and_b64 exec, exec, vcc
	v_lshlrev_b32_e32 v11, 12, v122
	s_mov_b32 s7, 0x3ff000
	v_lshl_add_u32 v10, v10, 2, v40
	v_and_or_b32 v11, v11, s7, v6
	ds_write_b32 v10, v11

.LBB0_2703:
	v_cmp_ge_u32_e64 s[42:43], v113, v5
	v_cmp_lt_u32_e64 s[44:45], v112, v5
	v_cmp_lt_u32_e64 s[46:47], v111, v5
	v_cmp_lt_u32_e64 s[48:49], v110, v5
	v_cndmask_b32_e64 v7, 0, v204, s[42:43]
	v_cndmask_b32_e64 v8, v205, 0, s[44:45]
	v_cndmask_b32_e64 v208, v206, 0, s[46:47]
	v_cndmask_b32_e64 v9, v207, 0, s[48:49]
	v_or_b32_e32 v7, v8, v7
	v_or3_b32 v7, v7, v208, v9
	v_cmp_ne_u32_e32 vcc, 0, v7
	s_and_saveexec_b64 s[0:1], vcc
	ds_or_b32 v203, v7 offset:224
	s_or_b64 exec, exec, s[0:1]
	v_xor_b32_e32 v8, v3, v111
	v_xor_b32_e32 v7, v3, v110
	v_xor_b32_e32 v10, v3, v113
	v_xor_b32_e32 v9, v3, v112
	v_min_u32_e32 v11, v8, v7
	v_min3_u32 v11, v10, v9, v11
	v_cmp_gt_u32_e32 vcc, s27, v11
	s_and_b64 s[8:9], s[40:41], vcc
	s_and_saveexec_b64 s[0:1], s[8:9]
	s_cbranch_execz .LBB0_2718
	v_add_u32_e32 v6, 0x700, v41
	v_cmp_gt_u32_e32 vcc, s27, v10
	s_and_saveexec_b64 s[8:9], vcc
	s_cbranch_execz .LBB0_2709
	ds_add_rtn_u32 v10, v2, v186
	s_waitcnt lgkmcnt(0)
	v_cmp_gt_u32_e32 vcc, 64, v10
	s_and_b64 exec, exec, vcc
	v_lshlrev_b32_e32 v11, 12, v113
	s_mov_b32 s7, 0x3ff000
	v_lshl_add_u32 v10, v10, 2, v40
	v_and_or_b32 v11, v11, s7, v6
	ds_write_b32 v10, v11

.LBB0_2720:
	v_cmp_ge_u32_e64 s[42:43], v106, v5
	v_cmp_lt_u32_e64 s[44:45], v104, v5
	v_cmp_lt_u32_e64 s[46:47], v103, v5
	v_cmp_lt_u32_e64 s[48:49], v102, v5
	v_cndmask_b32_e64 v7, 0, v204, s[42:43]
	v_cndmask_b32_e64 v8, v205, 0, s[44:45]
	v_cndmask_b32_e64 v208, v206, 0, s[46:47]
	v_cndmask_b32_e64 v9, v207, 0, s[48:49]
	v_or_b32_e32 v7, v8, v7
	v_or3_b32 v7, v7, v208, v9
	v_cmp_ne_u32_e32 vcc, 0, v7
	s_and_saveexec_b64 s[0:1], vcc
	ds_or_b32 v203, v7 offset:256
	s_or_b64 exec, exec, s[0:1]
	v_xor_b32_e32 v8, v3, v103
	v_xor_b32_e32 v7, v3, v102
	v_xor_b32_e32 v10, v3, v106
	v_xor_b32_e32 v9, v3, v104
	v_min_u32_e32 v11, v8, v7
	v_min3_u32 v11, v10, v9, v11
	v_cmp_gt_u32_e32 vcc, s27, v11
	s_and_b64 s[8:9], s[40:41], vcc
	s_and_saveexec_b64 s[0:1], s[8:9]
	s_cbranch_execz .LBB0_2735
	v_add_u32_e32 v6, 0x800, v41
	v_cmp_gt_u32_e32 vcc, s27, v10
	s_and_saveexec_b64 s[8:9], vcc
	s_cbranch_execz .LBB0_2726
	ds_add_rtn_u32 v10, v2, v186
	s_waitcnt lgkmcnt(0)
	v_cmp_gt_u32_e32 vcc, 64, v10
	s_and_b64 exec, exec, vcc
	v_lshlrev_b32_e32 v11, 12, v106
	s_mov_b32 s7, 0x3ff000
	v_lshl_add_u32 v10, v10, 2, v40
	v_and_or_b32 v11, v11, s7, v6
	ds_write_b32 v10, v11

.LBB0_2737:
	v_cmp_ge_u32_e64 s[42:43], v97, v5
	v_cmp_lt_u32_e64 s[44:45], v96, v5
	v_cmp_lt_u32_e64 s[46:47], v95, v5
	v_cmp_lt_u32_e64 s[48:49], v94, v5
	v_cndmask_b32_e64 v7, 0, v204, s[42:43]
	v_cndmask_b32_e64 v8, v205, 0, s[44:45]
	v_cndmask_b32_e64 v208, v206, 0, s[46:47]
	v_cndmask_b32_e64 v9, v207, 0, s[48:49]
	v_or_b32_e32 v7, v8, v7
	v_or3_b32 v7, v7, v208, v9
	v_cmp_ne_u32_e32 vcc, 0, v7
	s_and_saveexec_b64 s[0:1], vcc
	ds_or_b32 v203, v7 offset:288
	s_or_b64 exec, exec, s[0:1]
	v_xor_b32_e32 v8, v3, v95
	v_xor_b32_e32 v7, v3, v94
	v_xor_b32_e32 v10, v3, v97
	v_xor_b32_e32 v9, v3, v96
	v_min_u32_e32 v11, v8, v7
	v_min3_u32 v11, v10, v9, v11
	v_cmp_gt_u32_e32 vcc, s27, v11
	s_and_b64 s[8:9], s[40:41], vcc
	s_and_saveexec_b64 s[0:1], s[8:9]
	s_cbranch_execz .LBB0_2752
	v_add_u32_e32 v6, 0x900, v41
	v_cmp_gt_u32_e32 vcc, s27, v10
	s_and_saveexec_b64 s[8:9], vcc
	s_cbranch_execz .LBB0_2743
	ds_add_rtn_u32 v10, v2, v186
	s_waitcnt lgkmcnt(0)
	v_cmp_gt_u32_e32 vcc, 64, v10
	s_and_b64 exec, exec, vcc
	v_lshlrev_b32_e32 v11, 12, v97
	s_mov_b32 s7, 0x3ff000
	v_lshl_add_u32 v10, v10, 2, v40
	v_and_or_b32 v11, v11, s7, v6
	ds_write_b32 v10, v11

.LBB0_2754:
	v_cmp_ge_u32_e64 s[42:43], v89, v5
	v_cmp_lt_u32_e64 s[44:45], v88, v5
	v_cmp_lt_u32_e64 s[46:47], v87, v5
	v_cmp_lt_u32_e64 s[48:49], v86, v5
	v_cndmask_b32_e64 v7, 0, v204, s[42:43]
	v_cndmask_b32_e64 v8, v205, 0, s[44:45]
	v_cndmask_b32_e64 v208, v206, 0, s[46:47]
	v_cndmask_b32_e64 v9, v207, 0, s[48:49]
	v_or_b32_e32 v7, v8, v7
	v_or3_b32 v7, v7, v208, v9
	v_cmp_ne_u32_e32 vcc, 0, v7
	s_and_saveexec_b64 s[0:1], vcc
	ds_or_b32 v203, v7 offset:320
	s_or_b64 exec, exec, s[0:1]
	v_xor_b32_e32 v8, v3, v87
	v_xor_b32_e32 v7, v3, v86
	v_xor_b32_e32 v10, v3, v89
	v_xor_b32_e32 v9, v3, v88
	v_min_u32_e32 v11, v8, v7
	v_min3_u32 v11, v10, v9, v11
	v_cmp_gt_u32_e32 vcc, s27, v11
	s_and_b64 s[8:9], s[40:41], vcc
	s_and_saveexec_b64 s[0:1], s[8:9]
	s_cbranch_execz .LBB0_2769
	v_add_u32_e32 v6, 0xa00, v41
	v_cmp_gt_u32_e32 vcc, s27, v10
	s_and_saveexec_b64 s[8:9], vcc
	s_cbranch_execz .LBB0_2760
	ds_add_rtn_u32 v10, v2, v186
	s_waitcnt lgkmcnt(0)
	v_cmp_gt_u32_e32 vcc, 64, v10
	s_and_b64 exec, exec, vcc
	v_lshlrev_b32_e32 v11, 12, v89
	s_mov_b32 s7, 0x3ff000
	v_lshl_add_u32 v10, v10, 2, v40
	v_and_or_b32 v11, v11, s7, v6
	ds_write_b32 v10, v11

.LBB0_2771:
	v_cmp_ge_u32_e64 s[42:43], v81, v5
	v_cmp_lt_u32_e64 s[44:45], v80, v5
	v_cmp_lt_u32_e64 s[46:47], v79, v5
	v_cmp_lt_u32_e64 s[48:49], v78, v5
	v_cndmask_b32_e64 v7, 0, v204, s[42:43]
	v_cndmask_b32_e64 v8, v205, 0, s[44:45]
	v_cndmask_b32_e64 v208, v206, 0, s[46:47]
	v_cndmask_b32_e64 v9, v207, 0, s[48:49]
	v_or_b32_e32 v7, v8, v7
	v_or3_b32 v7, v7, v208, v9
	v_cmp_ne_u32_e32 vcc, 0, v7
	s_and_saveexec_b64 s[0:1], vcc
	ds_or_b32 v203, v7 offset:352
	s_or_b64 exec, exec, s[0:1]
	v_xor_b32_e32 v8, v3, v79
	v_xor_b32_e32 v7, v3, v78
	v_xor_b32_e32 v10, v3, v81
	v_xor_b32_e32 v9, v3, v80
	v_min_u32_e32 v11, v8, v7
	v_min3_u32 v11, v10, v9, v11
	v_cmp_gt_u32_e32 vcc, s27, v11
	s_and_b64 s[8:9], s[40:41], vcc
	s_and_saveexec_b64 s[0:1], s[8:9]
	s_cbranch_execz .LBB0_2786
	v_add_u32_e32 v6, 0xb00, v41
	v_cmp_gt_u32_e32 vcc, s27, v10
	s_and_saveexec_b64 s[8:9], vcc
	s_cbranch_execz .LBB0_2777
	ds_add_rtn_u32 v10, v2, v186
	s_waitcnt lgkmcnt(0)
	v_cmp_gt_u32_e32 vcc, 64, v10
	s_and_b64 exec, exec, vcc
	v_lshlrev_b32_e32 v11, 12, v81
	s_mov_b32 s7, 0x3ff000
	v_lshl_add_u32 v10, v10, 2, v40
	v_and_or_b32 v11, v11, s7, v6
	ds_write_b32 v10, v11

.LBB0_2788:
	v_cmp_ge_u32_e64 s[42:43], v73, v5
	v_cmp_lt_u32_e64 s[44:45], v72, v5
	v_cmp_lt_u32_e64 s[46:47], v71, v5
	v_cmp_lt_u32_e64 s[48:49], v70, v5
	v_cndmask_b32_e64 v7, 0, v204, s[42:43]
	v_cndmask_b32_e64 v8, v205, 0, s[44:45]
	v_cndmask_b32_e64 v208, v206, 0, s[46:47]
	v_cndmask_b32_e64 v9, v207, 0, s[48:49]
	v_or_b32_e32 v7, v8, v7
	v_or3_b32 v7, v7, v208, v9
	v_cmp_ne_u32_e32 vcc, 0, v7
	s_and_saveexec_b64 s[0:1], vcc
	ds_or_b32 v203, v7 offset:384
	s_or_b64 exec, exec, s[0:1]
	v_xor_b32_e32 v8, v3, v71
	v_xor_b32_e32 v7, v3, v70
	v_xor_b32_e32 v10, v3, v73
	v_xor_b32_e32 v9, v3, v72
	v_min_u32_e32 v11, v8, v7
	v_min3_u32 v11, v10, v9, v11
	v_cmp_gt_u32_e32 vcc, s27, v11
	s_and_b64 s[8:9], s[40:41], vcc
	s_and_saveexec_b64 s[0:1], s[8:9]
	s_cbranch_execz .LBB0_2803
	v_add_u32_e32 v6, 0xc00, v41
	v_cmp_gt_u32_e32 vcc, s27, v10
	s_and_saveexec_b64 s[8:9], vcc
	s_cbranch_execz .LBB0_2794
	ds_add_rtn_u32 v10, v2, v186
	s_waitcnt lgkmcnt(0)
	v_cmp_gt_u32_e32 vcc, 64, v10
	s_and_b64 exec, exec, vcc
	v_lshlrev_b32_e32 v11, 12, v73
	s_mov_b32 s7, 0x3ff000
	v_lshl_add_u32 v10, v10, 2, v40
	v_and_or_b32 v11, v11, s7, v6
	ds_write_b32 v10, v11

.LBB0_2805:
	v_cmp_ge_u32_e64 s[42:43], v65, v5
	v_cmp_lt_u32_e64 s[44:45], v64, v5
	v_cmp_lt_u32_e64 s[46:47], v63, v5
	v_cmp_lt_u32_e64 s[48:49], v62, v5
	v_cndmask_b32_e64 v7, 0, v204, s[42:43]
	v_cndmask_b32_e64 v8, v205, 0, s[44:45]
	v_cndmask_b32_e64 v208, v206, 0, s[46:47]
	v_cndmask_b32_e64 v9, v207, 0, s[48:49]
	v_or_b32_e32 v7, v8, v7
	v_or3_b32 v7, v7, v208, v9
	v_cmp_ne_u32_e32 vcc, 0, v7
	s_and_saveexec_b64 s[0:1], vcc
	ds_or_b32 v203, v7 offset:416
	s_or_b64 exec, exec, s[0:1]
	v_xor_b32_e32 v8, v3, v63
	v_xor_b32_e32 v7, v3, v62
	v_xor_b32_e32 v10, v3, v65
	v_xor_b32_e32 v9, v3, v64
	v_min_u32_e32 v11, v8, v7
	v_min3_u32 v11, v10, v9, v11
	v_cmp_gt_u32_e32 vcc, s27, v11
	s_and_b64 s[8:9], s[40:41], vcc
	s_and_saveexec_b64 s[0:1], s[8:9]
	s_cbranch_execz .LBB0_2820
	v_add_u32_e32 v6, 0xd00, v41
	v_cmp_gt_u32_e32 vcc, s27, v10
	s_and_saveexec_b64 s[8:9], vcc
	s_cbranch_execz .LBB0_2811
	ds_add_rtn_u32 v10, v2, v186
	s_waitcnt lgkmcnt(0)
	v_cmp_gt_u32_e32 vcc, 64, v10
	s_and_b64 exec, exec, vcc
	v_lshlrev_b32_e32 v11, 12, v65
	s_mov_b32 s7, 0x3ff000
	v_lshl_add_u32 v10, v10, 2, v40
	v_and_or_b32 v11, v11, s7, v6
	ds_write_b32 v10, v11

.LBB0_2822:
	v_cmp_ge_u32_e64 s[42:43], v57, v5
	v_cmp_lt_u32_e64 s[44:45], v56, v5
	v_cmp_lt_u32_e64 s[46:47], v55, v5
	v_cmp_lt_u32_e64 s[48:49], v54, v5
	v_cndmask_b32_e64 v7, 0, v204, s[42:43]
	v_cndmask_b32_e64 v8, v205, 0, s[44:45]
	v_cndmask_b32_e64 v208, v206, 0, s[46:47]
	v_cndmask_b32_e64 v9, v207, 0, s[48:49]
	v_or_b32_e32 v7, v8, v7
	v_or3_b32 v7, v7, v208, v9
	v_cmp_ne_u32_e32 vcc, 0, v7
	s_and_saveexec_b64 s[0:1], vcc
	ds_or_b32 v203, v7 offset:448
	s_or_b64 exec, exec, s[0:1]
	v_xor_b32_e32 v8, v3, v55
	v_xor_b32_e32 v7, v3, v54
	v_xor_b32_e32 v10, v3, v57
	v_xor_b32_e32 v9, v3, v56
	v_min_u32_e32 v11, v8, v7
	v_min3_u32 v11, v10, v9, v11
	v_cmp_gt_u32_e32 vcc, s27, v11
	s_and_b64 s[8:9], s[40:41], vcc
	s_and_saveexec_b64 s[0:1], s[8:9]
	s_cbranch_execz .LBB0_2837
	v_add_u32_e32 v6, 0xe00, v41
	v_cmp_gt_u32_e32 vcc, s27, v10
	s_and_saveexec_b64 s[8:9], vcc
	s_cbranch_execz .LBB0_2828
	ds_add_rtn_u32 v10, v2, v186
	s_waitcnt lgkmcnt(0)
	v_cmp_gt_u32_e32 vcc, 64, v10
	s_and_b64 exec, exec, vcc
	v_lshlrev_b32_e32 v11, 12, v57
	s_mov_b32 s7, 0x3ff000
	v_lshl_add_u32 v10, v10, 2, v40
	v_and_or_b32 v11, v11, s7, v6
	ds_write_b32 v10, v11

.LBB0_2839:
	v_cmp_ge_u32_e64 s[42:43], v49, v5
	v_cmp_lt_u32_e64 s[44:45], v48, v5
	v_cmp_lt_u32_e64 s[46:47], v47, v5
	v_cmp_lt_u32_e64 s[48:49], v46, v5
	v_cndmask_b32_e64 v7, 0, v204, s[42:43]
	v_cndmask_b32_e64 v8, v205, 0, s[44:45]
	v_cndmask_b32_e64 v208, v206, 0, s[46:47]
	v_cndmask_b32_e64 v9, v207, 0, s[48:49]
	v_or_b32_e32 v7, v8, v7
	v_or3_b32 v7, v7, v208, v9
	v_cmp_ne_u32_e32 vcc, 0, v7
	s_and_saveexec_b64 s[0:1], vcc
	ds_or_b32 v203, v7 offset:480
	s_or_b64 exec, exec, s[0:1]
	v_xor_b32_e32 v8, v3, v47
	v_xor_b32_e32 v7, v3, v46
	v_xor_b32_e32 v10, v3, v49
	v_xor_b32_e32 v9, v3, v48
	v_min_u32_e32 v11, v8, v7
	v_min3_u32 v11, v10, v9, v11
	v_cmp_gt_u32_e32 vcc, s27, v11
	s_and_b64 s[8:9], s[40:41], vcc
	s_and_saveexec_b64 s[0:1], s[8:9]
	s_cbranch_execz .LBB0_2854
	v_add_u32_e32 v6, 0xf00, v41
	v_cmp_gt_u32_e32 vcc, s27, v10
	s_and_saveexec_b64 s[8:9], vcc
	s_cbranch_execz .LBB0_2845
	ds_add_rtn_u32 v10, v2, v186
	s_waitcnt lgkmcnt(0)
	v_cmp_gt_u32_e32 vcc, 64, v10
	s_and_b64 exec, exec, vcc
	v_lshlrev_b32_e32 v11, 12, v49
	s_mov_b32 s7, 0x3ff000
	v_lshl_add_u32 v10, v10, 2, v40
	v_and_or_b32 v11, v11, s7, v6
	ds_write_b32 v10, v11
